# speedup vs baseline: 1.0043x; 1.0043x over previous
; __device__ __forceinline__ unsigned cvtpk(float lo, float hi) { unsigned r; asm("v_cvt_pk_bf16_f32 %0, %1, %2" : "=v"(r) : "v"(lo), "v"(hi)); return r; }
; template <int X> __device__ __forceinline__ float sxor(float v) { return __int_as_float(__builtin_amdgcn_ds_swizzle(__float_as_int(v), 0x1F | (X << 10))); }
; __device__ __forceinline__ float sxor32sum(float v) { auto r = __builtin_amdgcn_permlane32_swap(__float_as_uint(v), __float_as_uint(v), false, false); return __uint_as_float(r[0]) + __uint_as_float(r[1]); }
; __device__ __forceinline__ float red16(float v) { v += sxor<1>(v); v += sxor<2>(v); v += sxor<4>(v); v += sxor<8>(v); return v; }
; __device__ __forceinline__ void prep_phase(const Params& P, const int wv) {
;     ...
;           { float ss = 0.f;
; #pragma unroll
;             for (int i = 0; i < 4; ++i) { const f32x4 v = va[i]; ss += v[0] * v[0] + v[1] * v[1] + v[2] * v[2] + v[3] * v[3];
;                 *(u32x2*)(xb + (size_t)row * 1024 + i * 256 + lane * 4) = u32x2{cvtpk(v[0], v[1]), cvtpk(v[2], v[3])}; }
;             ss = sxor32sum(ss); ss = red16(ss); ss += sxor<16>(ss);
;             if (lane < 16) rowss[(size_t)row * 16 + lane] = lane == 0 ? ss : 0.f; }
.LBB0_241:
	s_or_b64 exec, exec, s[12:13]
	s_and_saveexec_b64 s[12:13], s[4:5]
	s_cbranch_execz .LBB0_236
	v_mul_f32_e32 v18, v15, v15
	v_mul_f32_e32 v19, v11, v11
	v_fmac_f32_e32 v18, v14, v14
	v_fmac_f32_e32 v19, v10, v10
	v_fmac_f32_e32 v18, v16, v16
	v_fmac_f32_e32 v19, v12, v12
	v_fmac_f32_e32 v18, v17, v17
	v_fmac_f32_e32 v19, v13, v13
	v_add_f32_e32 v18, v19, v18
	v_mul_f32_e32 v19, v7, v7
	v_fmac_f32_e32 v19, v6, v6
	v_fmac_f32_e32 v19, v8, v8
	v_fmac_f32_e32 v19, v9, v9
	v_add_f32_e32 v18, v19, v18
	v_mul_f32_e32 v19, v3, v3
	v_fmac_f32_e32 v19, v2, v2
	v_fmac_f32_e32 v19, v4, v4
	v_fmac_f32_e32 v19, v5, v5
	v_add_f32_e32 v18, v19, v18
	v_mov_b32_e32 v19, v18
	s_nop 1
	v_permlane32_swap_b32_e32 v18, v19
	v_add_f32_e32 v18, v18, v19
	s_waitcnt lgkmcnt(0)
	s_nop 1
	v_add_f32_dpp v22, v18, v18 quad_perm:[1,0,3,2] row_mask:0xf bank_mask:0xf
	ds_swizzle_b32 v23, v22 offset:swizzle(SWAP,2)
	v_lshlrev_b64 v[18:19], 11, v[42:43]
	v_lshl_add_u64 v[20:21], v[36:37], 0, v[18:19]
	v_cvt_pk_bf16_f32 v18, v14, v15
	v_cvt_pk_bf16_f32 v19, v16, v17
	s_waitcnt lgkmcnt(0)
	v_add_f32_e32 v22, v22, v23
	ds_swizzle_b32 v23, v22 offset:swizzle(SWAP,4)
	global_store_dwordx2 v[20:21], v[18:19], off
	v_cvt_pk_bf16_f32 v18, v10, v11
	v_cvt_pk_bf16_f32 v19, v12, v13
	global_store_dwordx2 v[20:21], v[18:19], off offset:512
	s_waitcnt lgkmcnt(0)
	v_add_f32_e32 v24, v22, v23
	ds_swizzle_b32 v25, v24 offset:swizzle(SWAP,8)
	v_cvt_pk_bf16_f32 v22, v6, v7
	v_cvt_pk_bf16_f32 v23, v8, v9
	global_store_dwordx2 v[20:21], v[22:23], off offset:1024
	v_cvt_pk_bf16_f32 v22, v2, v3
	s_waitcnt lgkmcnt(0)
	v_add_f32_e32 v18, v24, v25
	ds_swizzle_b32 v19, v18 offset:swizzle(SWAP,16)
	v_cvt_pk_bf16_f32 v23, v4, v5
	global_store_dwordx2 v[20:21], v[22:23], off offset:1536
	s_and_b64 exec, exec, vcc
	s_cbranch_execz .LBB0_236
	s_waitcnt lgkmcnt(0)
	v_add_f32_e32 v18, v18, v19
	v_cndmask_b32_e64 v20, 0, v18, s[0:1]
	v_lshlrev_b64 v[18:19], 6, v[42:43]
	v_lshl_add_u64 v[18:19], v[38:39], 0, v[18:19]
	global_store_dword v[18:19], v20, off
	s_branch .LBB0_236

; __device__ __forceinline__ unsigned cvtpk(float lo, float hi) { unsigned r; asm("v_cvt_pk_bf16_f32 %0, %1, %2" : "=v"(r) : "v"(lo), "v"(hi)); return r; }
; template <int X> __device__ __forceinline__ float sxor(float v) { return __int_as_float(__builtin_amdgcn_ds_swizzle(__float_as_int(v), 0x1F | (X << 10))); }
; __device__ __forceinline__ float sxor32sum(float v) { auto r = __builtin_amdgcn_permlane32_swap(__float_as_uint(v), __float_as_uint(v), false, false); return __uint_as_float(r[0]) + __uint_as_float(r[1]); }
; __device__ __forceinline__ float red16(float v) { v += sxor<1>(v); v += sxor<2>(v); v += sxor<4>(v); v += sxor<8>(v); return v; }
; __device__ __forceinline__ float blo(unsigned w) { return __uint_as_float(w << 16); }
; __device__ __forceinline__ float bhi(unsigned w) { return __uint_as_float(w & 0xffff0000u); }
; __device__ __forceinline__ void norm_phase(const Params& P, int layer, const int wv) {
;     ...
;     auto dorow = [&](int row, const u32x4 (&cy)[2], const u32x4 (&cx)[2]) {
;         float yv[16]; float ss = 0.f;
; #pragma unroll
;         for (int i = 0; i < 2; ++i) { const u32x4 w = cy[i];
; #pragma unroll
;             for (int k = 0; k < 4; ++k) { const float a = __uint_as_float(w[k] << 16), b = __uint_as_float(w[k] & 0xffff0000u);
;                 yv[i * 8 + k * 2] = a; yv[i * 8 + k * 2 + 1] = b; ss += a * a + b * b; } }
;         ss = sxor32sum(ss); ss = red16(ss); ss += sxor<16>(ss);
;         const float rs = rsqrtf(ss * (1.f / 1024.f) + EPS);
; #pragma unroll
;         for (int i = 0; i < 2; ++i) { const size_t o = (size_t)row * 1024 + i * 512 + lane * 8;
;             f32x4 xa, xc;
;             { const u32x4 xw = cx[i]; xa = f32x4{blo(xw[0]), bhi(xw[0]), blo(xw[1]), bhi(xw[1])}; xc = f32x4{blo(xw[2]), bhi(xw[2]), blo(xw[3]), bhi(xw[3])}; }
;             f32x4 ra, rc;
; #pragma unroll
;             for (int k = 0; k < 4; ++k) { ra[k] = xa[k] + yv[i * 8 + k] * rs * gq[i * 8 + k]; rc[k] = xc[k] + yv[i * 8 + 4 + k] * rs * gq[i * 8 + 4 + k]; }
;             *(u32x4*)(xb + o) = u32x4{cvtpk(ra[0], ra[1]), cvtpk(ra[2], ra[3]), cvtpk(rc[0], rc[1]), cvtpk(rc[2], rc[3])}; } };
.LBB0_331:
	s_or_b64 exec, exec, s[14:15]
	v_lshlrev_b32_e32 v74, 16, v46
	v_and_b32_e32 v46, 0xffff0000, v46
	v_lshlrev_b32_e32 v75, 16, v47
	v_and_b32_e32 v47, 0xffff0000, v47
	v_mul_f32_e32 v71, v46, v46
	v_mul_f32_e32 v78, v47, v47
	v_fmac_f32_e32 v71, v74, v74
	v_fmac_f32_e32 v78, v75, v75
	v_add_f32_e32 v71, v71, v78
	v_lshlrev_b32_e32 v78, 16, v48
	v_and_b32_e32 v48, 0xffff0000, v48
	v_mul_f32_e32 v79, v48, v48
	v_fmac_f32_e32 v79, v78, v78
	v_add_f32_e32 v71, v79, v71
	v_lshlrev_b32_e32 v79, 16, v49
	v_and_b32_e32 v49, 0xffff0000, v49
	v_mul_f32_e32 v80, v49, v49
	v_fmac_f32_e32 v80, v79, v79
	v_and_b32_e32 v81, 0xffff0000, v42
	v_add_f32_e32 v71, v80, v71
	v_lshlrev_b32_e32 v80, 16, v42
	v_mul_f32_e32 v42, v81, v81
	v_and_b32_e32 v83, 0xffff0000, v43
	v_fmac_f32_e32 v42, v80, v80
	v_lshlrev_b32_e32 v82, 16, v43
	v_mul_f32_e32 v43, v83, v83
	v_add_f32_e32 v42, v42, v71
	v_fmac_f32_e32 v43, v82, v82
	v_lshlrev_b32_e32 v84, 16, v44
	v_and_b32_e32 v44, 0xffff0000, v44
	v_add_f32_e32 v42, v43, v42
	v_mul_f32_e32 v43, v44, v44
	v_fmac_f32_e32 v43, v84, v84
	v_lshlrev_b32_e32 v85, 16, v45
	v_and_b32_e32 v45, 0xffff0000, v45
	v_add_f32_e32 v42, v43, v42
	v_mul_f32_e32 v43, v45, v45
	v_fmac_f32_e32 v43, v85, v85
	v_add_f32_e32 v42, v43, v42
	v_mov_b32_e32 v43, v42
	s_nop 1
	v_permlane32_swap_b32_e32 v42, v43
	v_add_f32_e32 v42, v42, v43
	ds_swizzle_b32 v43, v42 offset:swizzle(SWAP,1)
	v_ashrrev_i32_e32 v71, 31, v70
	v_lshlrev_b32_e32 v88, 16, v28
	v_and_b32_e32 v28, 0xffff0000, v28
	v_lshlrev_b32_e32 v87, 16, v27
	s_waitcnt lgkmcnt(0)
	v_add_f32_e32 v42, v42, v43
	ds_swizzle_b32 v43, v42 offset:swizzle(SWAP,2)
	v_lshlrev_b32_e32 v89, 16, v29
	v_and_b32_e32 v27, 0xffff0000, v27
	v_and_b32_e32 v29, 0xffff0000, v29
	s_waitcnt lgkmcnt(0)
	v_add_f32_e32 v42, v42, v43
	s_waitcnt lgkmcnt(0)
	s_nop 1
	v_add_f32_dpp v42, v42, v42 row_half_mirror row_mask:0xf bank_mask:0xf
	s_waitcnt lgkmcnt(0)
	s_nop 1
	v_add_f32_dpp v42, v42, v42 row_mirror row_mask:0xf bank_mask:0xf
	ds_swizzle_b32 v43, v42 offset:swizzle(SWAP,16)
	s_waitcnt lgkmcnt(0)
	v_add_f32_e32 v42, v42, v43
	v_fmamk_f32 v42, v42, 0x3a800000, v182
	v_mul_f32_e32 v43, 0x4b800000, v42
	v_cmp_gt_f32_e32 vcc, s44, v42
	s_nop 1
	v_cndmask_b32_e32 v42, v42, v43, vcc
	v_rsq_f32_e32 v42, v42
	s_nop 0
	v_mul_f32_e32 v43, 0x45800000, v42
	v_cndmask_b32_e32 v86, v42, v43, vcc
	v_lshlrev_b64 v[42:43], 11, v[70:71]
	v_lshlrev_b32_e32 v71, 16, v26
	v_and_b32_e32 v26, 0xffff0000, v26
	v_mul_f32_e32 v46, v86, v46
	v_fmac_f32_e32 v26, v7, v46
	v_mul_f32_e32 v46, v86, v48
	v_fmac_f32_e32 v28, v3, v46
	v_mul_f32_e32 v46, v86, v75
	v_fmac_f32_e32 v87, v8, v46
	v_mul_f32_e32 v46, v86, v79
	v_mul_f32_e32 v74, v86, v74
	v_fmac_f32_e32 v89, v4, v46
	v_mul_f32_e32 v46, v86, v47
	v_fmac_f32_e32 v71, v6, v74
	v_mul_f32_e32 v74, v86, v78
	v_fmac_f32_e32 v27, v9, v46
	v_mul_f32_e32 v46, v86, v49
	v_fmac_f32_e32 v88, v2, v74
	v_fmac_f32_e32 v29, v5, v46
	v_cvt_pk_bf16_f32 v28, v88, v28
	v_lshl_add_u64 v[42:43], v[66:67], 0, v[42:43]
	v_cvt_pk_bf16_f32 v26, v71, v26
	v_cvt_pk_bf16_f32 v27, v87, v27
	v_cvt_pk_bf16_f32 v29, v89, v29
	global_store_dwordx4 v[42:43], v[26:29], off
	v_mul_f32_e32 v44, v86, v44
	v_mul_f32_e32 v46, v86, v80
	v_lshlrev_b32_e32 v28, 16, v20
	v_and_b32_e32 v20, 0xffff0000, v20
	v_lshlrev_b32_e32 v27, 16, v19
	v_fmac_f32_e32 v20, v11, v44
	v_mul_f32_e32 v44, v86, v82
	v_lshlrev_b32_e32 v26, 16, v18
	v_lshlrev_b32_e32 v29, 16, v21
	v_fmac_f32_e32 v27, v16, v44
	v_mul_f32_e32 v44, v86, v85
	v_and_b32_e32 v19, 0xffff0000, v19
	v_fmac_f32_e32 v26, v14, v46
	v_mul_f32_e32 v46, v86, v84
	v_fmac_f32_e32 v29, v12, v44
	v_mul_f32_e32 v44, v86, v83
	v_and_b32_e32 v18, 0xffff0000, v18
	v_and_b32_e32 v21, 0xffff0000, v21
	v_fmac_f32_e32 v28, v10, v46
	v_mul_f32_e32 v46, v86, v81
	v_fmac_f32_e32 v19, v17, v44
	v_mul_f32_e32 v44, v86, v45
	v_fmac_f32_e32 v18, v15, v46
	v_fmac_f32_e32 v21, v13, v44
	v_cvt_pk_bf16_f32 v18, v26, v18
	v_cvt_pk_bf16_f32 v19, v27, v19
	v_cvt_pk_bf16_f32 v20, v28, v20
	v_cvt_pk_bf16_f32 v21, v29, v21
	global_store_dwordx4 v[42:43], v[18:21], off offset:1024
	s_waitcnt vmcnt(4)
	v_mov_b64_e32 v[26:27], v[54:55]
	v_mov_b64_e32 v[46:47], v[50:51]
	s_waitcnt vmcnt(2)
	v_mov_b64_e32 v[18:19], v[62:63]
	v_mov_b64_e32 v[42:43], v[58:59]
	v_mov_b64_e32 v[28:29], v[56:57]
	v_mov_b64_e32 v[20:21], v[64:65]
	v_mov_b64_e32 v[48:49], v[52:53]
	v_mov_b64_e32 v[44:45], v[60:61]

; __device__ __forceinline__ unsigned cvtpk(float lo, float hi) { unsigned r; asm("v_cvt_pk_bf16_f32 %0, %1, %2" : "=v"(r) : "v"(lo), "v"(hi)); return r; }
; template <int X> __device__ __forceinline__ float sxor(float v) { return __int_as_float(__builtin_amdgcn_ds_swizzle(__float_as_int(v), 0x1F | (X << 10))); }
; __device__ __forceinline__ float red16(float v) { v += sxor<1>(v); v += sxor<2>(v); v += sxor<4>(v); v += sxor<8>(v); return v; }
; __device__ __forceinline__ void norm_phase(const Params& P, int layer, const int wv) {
;     ...
;     auto dorow = [&](int row, const u32x4 (&cy)[2], const u32x4 (&cx)[2]) {
;         float yv[16]; float ss = 0.f;
; #pragma unroll
;         for (int i = 0; i < 2; ++i) { const u32x4 w = cy[i];
; #pragma unroll
;             for (int k = 0; k < 4; ++k) { const float a = __uint_as_float(w[k] << 16), b = __uint_as_float(w[k] & 0xffff0000u);
;                 yv[i * 8 + k * 2] = a; yv[i * 8 + k * 2 + 1] = b; ss += a * a + b * b; } }
;         ss = sxor32sum(ss); ss = red16(ss); ss += sxor<16>(ss);
;         const float rs = rsqrtf(ss * (1.f / 1024.f) + EPS);
; #pragma unroll
;         for (int i = 0; i < 2; ++i) { const size_t o = (size_t)row * 1024 + i * 512 + lane * 8;
;             f32x4 xa, xc;
;             { const u32x4 xw = cx[i]; xa = f32x4{blo(xw[0]), bhi(xw[0]), blo(xw[1]), bhi(xw[1])}; xc = f32x4{blo(xw[2]), bhi(xw[2]), blo(xw[3]), bhi(xw[3])}; }
;             f32x4 ra, rc;
; #pragma unroll
;             for (int k = 0; k < 4; ++k) { ra[k] = xa[k] + yv[i * 8 + k] * rs * gq[i * 8 + k]; rc[k] = xc[k] + yv[i * 8 + 4 + k] * rs * gq[i * 8 + 4 + k]; }
;             *(u32x4*)(xb + o) = u32x4{cvtpk(ra[0], ra[1]), cvtpk(ra[2], ra[3]), cvtpk(rc[0], rc[1]), cvtpk(rc[2], rc[3])}; } };
;     u32x4 yA[2], xA[2], yB[2], xB[2];
;     const int rowb = blockIdx.x * 8 + wid;
;     ldrow(rowb, yA, xA); ldrow(rowb + rstep, yB, xB);
;     for (int row = rowb; row < T; row += 2 * rstep) {
;         u32x4 cy[2], cx[2];
; #pragma unroll
;         for (int i = 0; i < 2; ++i) { cy[i] = yA[i]; cx[i] = xA[i]; }
;         ldrow(row + 2 * rstep, yA, xA);
;         dorow(row, cy, cx);
;         if (row + rstep < T) {
; #pragma unroll
;             for (int i = 0; i < 2; ++i) { cy[i] = yB[i]; cx[i] = xB[i]; }
;             ldrow(row + 3 * rstep, yB, xB);
;             dorow(row + rstep, cy, cx); }
.LBB0_335:
	s_or_b64 exec, exec, s[12:13]
	v_lshlrev_b32_e32 v71, 16, v62
	v_and_b32_e32 v62, 0xffff0000, v62
	v_lshlrev_b32_e32 v78, 16, v63
	v_and_b32_e32 v63, 0xffff0000, v63
	v_mul_f32_e32 v75, v62, v62
	v_mul_f32_e32 v79, v63, v63
	v_fmac_f32_e32 v75, v71, v71
	v_fmac_f32_e32 v79, v78, v78
	v_add_f32_e32 v75, v75, v79
	v_lshlrev_b32_e32 v79, 16, v64
	v_and_b32_e32 v64, 0xffff0000, v64
	v_mul_f32_e32 v80, v64, v64
	v_fmac_f32_e32 v80, v79, v79
	v_add_f32_e32 v75, v80, v75
	v_lshlrev_b32_e32 v80, 16, v65
	v_and_b32_e32 v65, 0xffff0000, v65
	v_mul_f32_e32 v81, v65, v65
	v_fmac_f32_e32 v81, v80, v80
	v_and_b32_e32 v82, 0xffff0000, v58
	v_add_f32_e32 v75, v81, v75
	v_lshlrev_b32_e32 v81, 16, v58
	v_mul_f32_e32 v58, v82, v82
	v_fmac_f32_e32 v58, v81, v81
	v_and_b32_e32 v83, 0xffff0000, v59
	v_add_f32_e32 v58, v58, v75
	v_lshlrev_b32_e32 v75, 16, v59
	v_mul_f32_e32 v59, v83, v83
	v_fmac_f32_e32 v59, v75, v75
	v_lshlrev_b32_e32 v84, 16, v60
	v_and_b32_e32 v60, 0xffff0000, v60
	v_add_f32_e32 v58, v59, v58
	v_mul_f32_e32 v59, v60, v60
	v_fmac_f32_e32 v59, v84, v84
	v_lshlrev_b32_e32 v85, 16, v61
	v_and_b32_e32 v61, 0xffff0000, v61
	v_add_f32_e32 v58, v59, v58
	v_mul_f32_e32 v59, v61, v61
	v_fmac_f32_e32 v59, v85, v85
	v_add_f32_e32 v58, v59, v58
	v_mov_b32_e32 v59, v58
	s_nop 1
	v_permlane32_swap_b32_e32 v58, v59
	v_add_f32_e32 v58, v58, v59
	ds_swizzle_b32 v59, v58 offset:swizzle(SWAP,1)
	v_lshlrev_b32_e32 v87, 16, v56
	v_and_b32_e32 v56, 0xffff0000, v56
	v_lshlrev_b32_e32 v88, 16, v57
	v_and_b32_e32 v57, 0xffff0000, v57
	s_waitcnt lgkmcnt(0)
	v_add_f32_e32 v58, v58, v59
	ds_swizzle_b32 v59, v58 offset:swizzle(SWAP,2)
	s_mov_b32 s12, 0x8000
	s_waitcnt lgkmcnt(0)
	v_add_f32_e32 v58, v58, v59
	s_waitcnt lgkmcnt(0)
	s_nop 1
	v_add_f32_dpp v58, v58, v58 row_half_mirror row_mask:0xf bank_mask:0xf
	s_waitcnt lgkmcnt(0)
	s_nop 1
	v_add_f32_dpp v58, v58, v58 row_mirror row_mask:0xf bank_mask:0xf
	ds_swizzle_b32 v59, v58 offset:swizzle(SWAP,16)
	s_waitcnt lgkmcnt(0)
	v_add_f32_e32 v58, v58, v59
	v_fmamk_f32 v58, v58, 0x3a800000, v182
	v_mul_f32_e32 v59, 0x4b800000, v58
	v_cmp_gt_f32_e32 vcc, s44, v58
	s_nop 1
	v_cndmask_b32_e32 v58, v58, v59, vcc
	v_rsq_f32_e32 v58, v58
	s_nop 0
	v_mul_f32_e32 v59, 0x45800000, v58
	v_cndmask_b32_e32 v86, v58, v59, vcc
	v_lshlrev_b32_e32 v58, 16, v54
	v_and_b32_e32 v54, 0xffff0000, v54
	v_mul_f32_e32 v62, v86, v62
	v_fmac_f32_e32 v54, v7, v62
	v_mul_f32_e32 v62, v86, v64
	v_lshlrev_b32_e32 v59, 16, v55
	v_fmac_f32_e32 v56, v3, v62
	v_mul_f32_e32 v62, v86, v78
	v_fmac_f32_e32 v59, v8, v62
	v_mul_f32_e32 v62, v86, v80
	v_and_b32_e32 v55, 0xffff0000, v55
	v_mul_f32_e32 v71, v86, v71
	v_fmac_f32_e32 v88, v4, v62
	v_mul_f32_e32 v62, v86, v63
	v_fmac_f32_e32 v58, v6, v71
	v_fmac_f32_e32 v55, v9, v62
	v_cvt_pk_bf16_f32 v54, v58, v54
	v_cvt_pk_bf16_f32 v55, v59, v55
	v_lshl_add_u64 v[58:59], v[68:69], 0, v[0:1]
	v_mul_f32_e32 v71, v86, v79
	v_mul_f32_e32 v62, v86, v65
	v_add_co_u32_e32 v58, vcc, s85, v58
	v_fmac_f32_e32 v87, v2, v71
	v_fmac_f32_e32 v57, v5, v62
	v_cvt_pk_bf16_f32 v56, v87, v56
	v_addc_co_u32_e32 v59, vcc, 0, v59, vcc
	v_cvt_pk_bf16_f32 v57, v88, v57
	global_store_dwordx4 v[58:59], v[54:57], off
	v_mul_f32_e32 v60, v86, v60
	v_mul_f32_e32 v62, v86, v81
	v_lshlrev_b32_e32 v56, 16, v52
	v_and_b32_e32 v52, 0xffff0000, v52
	v_lshlrev_b32_e32 v55, 16, v51
	v_fmac_f32_e32 v52, v11, v60
	v_mul_f32_e32 v60, v86, v75
	v_lshlrev_b32_e32 v54, 16, v50
	v_lshlrev_b32_e32 v57, 16, v53
	v_fmac_f32_e32 v55, v16, v60
	v_mul_f32_e32 v60, v86, v85
	v_and_b32_e32 v51, 0xffff0000, v51
	v_fmac_f32_e32 v54, v14, v62
	v_mul_f32_e32 v62, v86, v84
	v_fmac_f32_e32 v57, v12, v60
	v_mul_f32_e32 v60, v86, v83
	v_and_b32_e32 v50, 0xffff0000, v50
	v_and_b32_e32 v53, 0xffff0000, v53
	v_fmac_f32_e32 v56, v10, v62
	v_mul_f32_e32 v62, v86, v82
	v_fmac_f32_e32 v51, v17, v60
	v_mul_f32_e32 v60, v86, v61
	v_fmac_f32_e32 v50, v15, v62
	v_fmac_f32_e32 v53, v13, v60
	v_cmp_gt_i32_e32 vcc, s12, v70
	v_cvt_pk_bf16_f32 v50, v54, v50
	v_cvt_pk_bf16_f32 v51, v55, v51
	v_cvt_pk_bf16_f32 v52, v56, v52
	v_cvt_pk_bf16_f32 v53, v57, v53
	global_store_dwordx4 v[58:59], v[50:53], off offset:1024
	s_and_saveexec_b64 s[12:13], vcc
	s_cbranch_execz .LBB0_332
	v_readlane_b32 s14, v253, 57
	s_mul_i32 s14, s14, 24
	v_mov_b64_e32 v[60:61], v[44:45]
	v_add_u32_e32 v74, s14, v74
	s_mov_b32 s14, 0x8000
	v_mov_b64_e32 v[52:53], v[48:49]
	v_mov_b64_e32 v[64:65], v[20:21]
	v_mov_b64_e32 v[56:57], v[28:29]
	v_readlane_b32 s15, v253, 58
	v_cmp_gt_i32_e32 vcc, s14, v74
	v_mov_b64_e32 v[58:59], v[42:43]
	v_mov_b64_e32 v[50:51], v[46:47]
	v_mov_b64_e32 v[62:63], v[18:19]
	v_mov_b64_e32 v[54:55], v[26:27]
	s_and_saveexec_b64 s[14:15], vcc
	s_cbranch_execz .LBB0_331
	v_ashrrev_i32_e32 v75, 31, v74
	v_lshlrev_b64 v[58:59], 11, v[74:75]
	v_lshl_or_b32 v58, v76, 1, v58
	v_lshl_add_u64 v[50:51], s[2:3], 0, v[58:59]
	v_lshl_add_u64 v[54:55], s[6:7], 0, v[58:59]
	v_or_b32_e32 v58, 0x400, v58
	v_lshl_add_u64 v[60:61], s[2:3], 0, v[58:59]
	v_lshl_add_u64 v[62:63], s[6:7], 0, v[58:59]
	global_load_dwordx4 v[50:53], v[50:51], off
	s_nop 0
	global_load_dwordx4 v[54:57], v[54:55], off
	s_nop 0
	global_load_dwordx4 v[58:61], v[60:61], off
	s_nop 0
	global_load_dwordx4 v[62:65], v[62:63], off
	s_branch .LBB0_331

; __device__ __forceinline__ unsigned cvtpk(float lo, float hi) { unsigned r; asm("v_cvt_pk_bf16_f32 %0, %1, %2" : "=v"(r) : "v"(lo), "v"(hi)); return r; }
; __device__ __forceinline__ float red32(float v) { v += sxor<1>(v); v += sxor<2>(v); v += sxor<4>(v); v += sxor<8>(v); v += sxor<16>(v); return v; }
; __device__ __forceinline__ float blo(unsigned w) { return __uint_as_float(w << 16); }
; __device__ __forceinline__ float bhi(unsigned w) { return __uint_as_float(w & 0xffff0000u); }
; template <int kind> __device__ __forceinline__ void gemm_phase_n(const Params& P, int layer, int b, const int wv) {
;     ...
;                 DRAIN_BEGIN const size_t t = tb + row; u16* up = U + t * 2048 + gb + chunk * 8;
;                     const u32x4 sgw = *(const u32x4*)up; const f32x4 g0 = *(const f32x4*)(gn + chunk * 8), g1 = *(const f32x4*)(gn + chunk * 8 + 4);
;                     float o0 = blo(w[0]), o1 = bhi(w[0]), o2 = blo(w[1]), o3 = bhi(w[1]), o4 = blo(w[2]), o5 = bhi(w[2]), o6 = blo(w[3]), o7 = bhi(w[3]);
;                     float ss = o0 * o0 + o1 * o1 + o2 * o2 + o3 * o3 + o4 * o4 + o5 * o5 + o6 * o6 + o7 * o7;
;                     *(u32x4*)up = u32x4{cvtpk(o0 * blo(sgw[0]) * g0[0], o1 * bhi(sgw[0]) * g0[1]), cvtpk(o2 * blo(sgw[1]) * g0[2], o3 * bhi(sgw[1]) * g0[3]),
;                                         cvtpk(o4 * blo(sgw[2]) * g1[0], o5 * bhi(sgw[2]) * g1[1]), cvtpk(o6 * blo(sgw[3]) * g1[2], o7 * bhi(sgw[3]) * g1[3])};
;                     ss = red32(ss); if (chunk == 0) *(f32x4*)(ssq + (t * 4 + h) * 8 + pn * 4) = f32x4{ss, 0.f, 0.f, 0.f};
;                 LOOP_END } break;
.LBB0_387:
	v_lshl_add_u64 v[32:33], v[6:7], 0, s[2:3]
	global_load_dwordx4 v[14:17], v[32:33], off
	global_load_dwordx4 v[20:23], v[4:5], off
	global_load_dwordx4 v[24:27], v[4:5], off offset:16
	v_add_u32_e32 v19, s12, v18
	ds_read_b128 v[28:31], v19
	s_waitcnt lgkmcnt(0)
	v_lshlrev_b32_e32 v3, 16, v28
	v_and_b32_e32 v28, 0xffff0000, v28
	v_mul_f32_e32 v0, v3, v3
	v_lshlrev_b32_e32 v34, 16, v29
	v_fmac_f32_e32 v0, v28, v28
	v_and_b32_e32 v29, 0xffff0000, v29
	v_fmac_f32_e32 v0, v34, v34
	v_lshlrev_b32_e32 v35, 16, v30
	v_fmac_f32_e32 v0, v29, v29
	v_and_b32_e32 v30, 0xffff0000, v30
	v_fmac_f32_e32 v0, v35, v35
	v_lshlrev_b32_e32 v36, 16, v31
	v_fmac_f32_e32 v0, v30, v30
	v_and_b32_e32 v31, 0xffff0000, v31
	v_fmac_f32_e32 v0, v36, v36
	v_fmac_f32_e32 v0, v31, v31
	s_waitcnt lgkmcnt(0)
	s_nop 1
	v_add_f32_dpp v0, v0, v0 quad_perm:[1,0,3,2] row_mask:0xf bank_mask:0xf
	s_waitcnt lgkmcnt(0)
	s_nop 1
	v_add_f32_dpp v0, v0, v0 quad_perm:[2,3,0,1] row_mask:0xf bank_mask:0xf
	s_waitcnt lgkmcnt(0)
	s_nop 1
	v_add_f32_dpp v0, v0, v0 row_half_mirror row_mask:0xf bank_mask:0xf
	s_waitcnt lgkmcnt(0)
	s_nop 1
	v_add_f32_dpp v0, v0, v0 row_mirror row_mask:0xf bank_mask:0xf
	ds_swizzle_b32 v2, v0 offset:swizzle(SWAP,16)
	s_waitcnt vmcnt(2)
	v_lshlrev_b32_e32 v37, 16, v14
	v_and_b32_e32 v14, 0xffff0000, v14
	v_lshlrev_b32_e32 v38, 16, v15
	v_and_b32_e32 v15, 0xffff0000, v15
	v_lshlrev_b32_e32 v39, 16, v16
	v_and_b32_e32 v16, 0xffff0000, v16
	v_lshlrev_b32_e32 v40, 16, v17
	v_and_b32_e32 v17, 0xffff0000, v17
	v_mul_f32_e32 v14, v14, v28
	v_mul_f32_e32 v15, v15, v29
	v_mul_f32_e32 v16, v16, v30
	v_mul_f32_e32 v17, v17, v31
	v_mul_f32_e32 v3, v37, v3
	v_mul_f32_e32 v28, v38, v34
	v_mul_f32_e32 v29, v39, v35
	v_mul_f32_e32 v30, v40, v36
	s_waitcnt vmcnt(1)
	v_mul_f32_e32 v14, v21, v14
	v_mul_f32_e32 v15, v23, v15
	s_waitcnt vmcnt(0)
	v_mul_f32_e32 v16, v25, v16
	v_mul_f32_e32 v17, v27, v17
	v_mul_f32_e32 v3, v20, v3
	v_mul_f32_e32 v20, v22, v28
	v_mul_f32_e32 v21, v24, v29
	v_mul_f32_e32 v22, v26, v30
	v_cvt_pk_bf16_f32 v14, v3, v14
	v_cvt_pk_bf16_f32 v15, v20, v15
	v_cvt_pk_bf16_f32 v16, v21, v16
	v_cvt_pk_bf16_f32 v17, v22, v17
	global_store_dwordx4 v[32:33], v[14:17], off
	s_and_saveexec_b64 s[10:11], s[4:5]
	s_cbranch_execz .LBB0_389
	v_lshl_add_u64 v[14:15], v[12:13], 0, s[2:3]
	s_waitcnt lgkmcnt(0)
	v_add_f32_e32 v0, v0, v2
	v_mov_b32_e32 v2, v1
	v_mov_b32_e32 v3, v1
	global_store_dwordx4 v[14:15], v[0:3], off
.LBB0_389:
	s_or_b64 exec, exec, s[10:11]
	v_lshl_add_u64 v[16:17], v[8:9], 0, s[2:3]
	v_add_co_u32_e32 v14, vcc, 0xcc10000, v16
	s_nop 1
	v_addc_co_u32_e32 v15, vcc, 0, v17, vcc
	global_load_dwordx4 v[20:23], v[14:15], off
	global_load_dwordx4 v[24:27], v[4:5], off
	global_load_dwordx4 v[28:31], v[4:5], off offset:16
	ds_read_b128 v[32:35], v19 offset:8704
	s_waitcnt lgkmcnt(0)
	v_lshlrev_b32_e32 v3, 16, v32
	v_and_b32_e32 v32, 0xffff0000, v32
	v_mul_f32_e32 v0, v3, v3
	v_lshlrev_b32_e32 v36, 16, v33
	v_fmac_f32_e32 v0, v32, v32
	v_and_b32_e32 v33, 0xffff0000, v33
	v_fmac_f32_e32 v0, v36, v36
	v_lshlrev_b32_e32 v37, 16, v34
	v_fmac_f32_e32 v0, v33, v33
	v_and_b32_e32 v34, 0xffff0000, v34
	v_fmac_f32_e32 v0, v37, v37
	v_lshlrev_b32_e32 v38, 16, v35
	v_fmac_f32_e32 v0, v34, v34
	v_and_b32_e32 v35, 0xffff0000, v35
	v_fmac_f32_e32 v0, v38, v38
	v_fmac_f32_e32 v0, v35, v35
	s_waitcnt lgkmcnt(0)
	s_nop 1
	v_add_f32_dpp v0, v0, v0 quad_perm:[1,0,3,2] row_mask:0xf bank_mask:0xf
	s_waitcnt lgkmcnt(0)
	s_nop 1
	v_add_f32_dpp v0, v0, v0 quad_perm:[2,3,0,1] row_mask:0xf bank_mask:0xf
	s_waitcnt lgkmcnt(0)
	s_nop 1
	v_add_f32_dpp v0, v0, v0 row_half_mirror row_mask:0xf bank_mask:0xf
	s_waitcnt lgkmcnt(0)
	s_nop 1
	v_add_f32_dpp v0, v0, v0 row_mirror row_mask:0xf bank_mask:0xf
	ds_swizzle_b32 v2, v0 offset:swizzle(SWAP,16)
	s_waitcnt vmcnt(2)
	v_lshlrev_b32_e32 v39, 16, v20
	v_and_b32_e32 v20, 0xffff0000, v20
	v_lshlrev_b32_e32 v40, 16, v21
	v_and_b32_e32 v21, 0xffff0000, v21
	v_lshlrev_b32_e32 v41, 16, v22
	v_and_b32_e32 v22, 0xffff0000, v22
	v_lshlrev_b32_e32 v42, 16, v23
	v_and_b32_e32 v23, 0xffff0000, v23
	v_mul_f32_e32 v20, v20, v32
	v_mul_f32_e32 v21, v21, v33
	v_mul_f32_e32 v22, v22, v34
	v_mul_f32_e32 v23, v23, v35
	v_mul_f32_e32 v3, v39, v3
	v_mul_f32_e32 v32, v40, v36
	v_mul_f32_e32 v33, v41, v37
	v_mul_f32_e32 v34, v42, v38
	s_waitcnt vmcnt(1)
	v_mul_f32_e32 v20, v25, v20
	v_mul_f32_e32 v21, v27, v21
	s_waitcnt vmcnt(0)
	v_mul_f32_e32 v22, v29, v22
	v_mul_f32_e32 v23, v31, v23
	v_mul_f32_e32 v3, v24, v3
	v_mul_f32_e32 v24, v26, v32
	v_mul_f32_e32 v25, v28, v33
	v_mul_f32_e32 v26, v30, v34
	v_cvt_pk_bf16_f32 v20, v3, v20
	v_cvt_pk_bf16_f32 v21, v24, v21
	v_cvt_pk_bf16_f32 v22, v25, v22
	v_cvt_pk_bf16_f32 v23, v26, v23
	global_store_dwordx4 v[14:15], v[20:23], off
	v_lshl_add_u64 v[14:15], v[10:11], 0, s[2:3]
	s_and_saveexec_b64 s[10:11], s[4:5]
	s_cbranch_execz .LBB0_391
	v_add_co_u32_e32 v20, vcc, 0x16200000, v14
	s_waitcnt lgkmcnt(0)
	v_add_f32_e32 v0, v0, v2
	v_addc_co_u32_e32 v21, vcc, 0, v15, vcc
	v_mov_b32_e32 v2, v1
	v_mov_b32_e32 v3, v1
	global_store_dwordx4 v[20:21], v[0:3], off offset:2048
; __device__ __forceinline__ unsigned cvtpk(float lo, float hi) { unsigned r; asm("v_cvt_pk_bf16_f32 %0, %1, %2" : "=v"(r) : "v"(lo), "v"(hi)); return r; }
; __device__ __forceinline__ float red32(float v) { v += sxor<1>(v); v += sxor<2>(v); v += sxor<4>(v); v += sxor<8>(v); v += sxor<16>(v); return v; }
; __device__ __forceinline__ float blo(unsigned w) { return __uint_as_float(w << 16); }
; __device__ __forceinline__ float bhi(unsigned w) { return __uint_as_float(w & 0xffff0000u); }
; template <int kind> __device__ __forceinline__ void gemm_phase_n(const Params& P, int layer, int b, const int wv) {
;     ...
;                 DRAIN_BEGIN const size_t t = tb + row; u16* up = U + t * 2048 + gb + chunk * 8;
;                     const u32x4 sgw = *(const u32x4*)up; const f32x4 g0 = *(const f32x4*)(gn + chunk * 8), g1 = *(const f32x4*)(gn + chunk * 8 + 4);
;                     float o0 = blo(w[0]), o1 = bhi(w[0]), o2 = blo(w[1]), o3 = bhi(w[1]), o4 = blo(w[2]), o5 = bhi(w[2]), o6 = blo(w[3]), o7 = bhi(w[3]);
;                     float ss = o0 * o0 + o1 * o1 + o2 * o2 + o3 * o3 + o4 * o4 + o5 * o5 + o6 * o6 + o7 * o7;
;                     *(u32x4*)up = u32x4{cvtpk(o0 * blo(sgw[0]) * g0[0], o1 * bhi(sgw[0]) * g0[1]), cvtpk(o2 * blo(sgw[1]) * g0[2], o3 * bhi(sgw[1]) * g0[3]),
;                                         cvtpk(o4 * blo(sgw[2]) * g1[0], o5 * bhi(sgw[2]) * g1[1]), cvtpk(o6 * blo(sgw[3]) * g1[2], o7 * bhi(sgw[3]) * g1[3])};
;                     ss = red32(ss); if (chunk == 0) *(f32x4*)(ssq + (t * 4 + h) * 8 + pn * 4) = f32x4{ss, 0.f, 0.f, 0.f};
;                 LOOP_END } break;
.LBB0_391:
	s_or_b64 exec, exec, s[10:11]
	v_add_co_u32_e32 v36, vcc, 0xcc20000, v16
	s_nop 1
	v_addc_co_u32_e32 v37, vcc, 0, v17, vcc
	global_load_dwordx4 v[20:23], v[36:37], off
	global_load_dwordx4 v[24:27], v[4:5], off
	global_load_dwordx4 v[28:31], v[4:5], off offset:16
	ds_read_b128 v[32:35], v19 offset:17408
	s_waitcnt lgkmcnt(0)
	v_lshlrev_b32_e32 v3, 16, v32
	v_and_b32_e32 v32, 0xffff0000, v32
	v_mul_f32_e32 v0, v3, v3
	v_lshlrev_b32_e32 v38, 16, v33
	v_fmac_f32_e32 v0, v32, v32
	v_and_b32_e32 v33, 0xffff0000, v33
	v_fmac_f32_e32 v0, v38, v38
	v_lshlrev_b32_e32 v39, 16, v34
	v_fmac_f32_e32 v0, v33, v33
	v_and_b32_e32 v34, 0xffff0000, v34
	v_fmac_f32_e32 v0, v39, v39
	v_lshlrev_b32_e32 v40, 16, v35
	v_fmac_f32_e32 v0, v34, v34
	v_and_b32_e32 v35, 0xffff0000, v35
	v_fmac_f32_e32 v0, v40, v40
	v_fmac_f32_e32 v0, v35, v35
	s_waitcnt lgkmcnt(0)
	s_nop 1
	v_add_f32_dpp v0, v0, v0 quad_perm:[1,0,3,2] row_mask:0xf bank_mask:0xf
	s_waitcnt lgkmcnt(0)
	s_nop 1
	v_add_f32_dpp v0, v0, v0 quad_perm:[2,3,0,1] row_mask:0xf bank_mask:0xf
	s_waitcnt lgkmcnt(0)
	s_nop 1
	v_add_f32_dpp v0, v0, v0 row_half_mirror row_mask:0xf bank_mask:0xf
	s_waitcnt lgkmcnt(0)
	s_nop 1
	v_add_f32_dpp v0, v0, v0 row_mirror row_mask:0xf bank_mask:0xf
	ds_swizzle_b32 v2, v0 offset:swizzle(SWAP,16)
	s_waitcnt vmcnt(2)
	v_lshlrev_b32_e32 v41, 16, v20
	v_and_b32_e32 v20, 0xffff0000, v20
	v_lshlrev_b32_e32 v42, 16, v21
	v_and_b32_e32 v21, 0xffff0000, v21
	v_lshlrev_b32_e32 v43, 16, v22
	v_and_b32_e32 v22, 0xffff0000, v22
	v_lshlrev_b32_e32 v44, 16, v23
	v_and_b32_e32 v23, 0xffff0000, v23
	v_mul_f32_e32 v20, v20, v32
	v_mul_f32_e32 v21, v21, v33
	v_mul_f32_e32 v22, v22, v34
	v_mul_f32_e32 v23, v23, v35
	v_mul_f32_e32 v3, v41, v3
	v_mul_f32_e32 v32, v42, v38
	v_mul_f32_e32 v33, v43, v39
	v_mul_f32_e32 v34, v44, v40
	s_waitcnt vmcnt(1)
	v_mul_f32_e32 v20, v25, v20
	v_mul_f32_e32 v21, v27, v21
	s_waitcnt vmcnt(0)
	v_mul_f32_e32 v22, v29, v22
	v_mul_f32_e32 v23, v31, v23
	v_mul_f32_e32 v3, v24, v3
	v_mul_f32_e32 v24, v26, v32
	v_mul_f32_e32 v25, v28, v33
	v_mul_f32_e32 v26, v30, v34
	v_cvt_pk_bf16_f32 v20, v3, v20
	v_cvt_pk_bf16_f32 v21, v24, v21
	v_cvt_pk_bf16_f32 v22, v25, v22
	v_cvt_pk_bf16_f32 v23, v26, v23
	global_store_dwordx4 v[36:37], v[20:23], off
	s_and_saveexec_b64 s[10:11], s[4:5]
	s_cbranch_execz .LBB0_393
	v_add_co_u32_e32 v20, vcc, 0x16201000, v14
	s_waitcnt lgkmcnt(0)
	v_add_f32_e32 v0, v0, v2
	v_addc_co_u32_e32 v21, vcc, 0, v15, vcc
	v_mov_b32_e32 v2, v1
	v_mov_b32_e32 v3, v1
	global_store_dwordx4 v[20:21], v[0:3], off
.LBB0_393:
	s_or_b64 exec, exec, s[10:11]
	v_add_co_u32_e32 v16, vcc, 0xcc30000, v16
	s_nop 1
	v_addc_co_u32_e32 v17, vcc, 0, v17, vcc
	global_load_dwordx4 v[20:23], v[16:17], off
	global_load_dwordx4 v[24:27], v[4:5], off
	global_load_dwordx4 v[28:31], v[4:5], off offset:16
	ds_read_b128 v[32:35], v19 offset:26112
	s_waitcnt lgkmcnt(0)
	v_lshlrev_b32_e32 v3, 16, v32
	v_and_b32_e32 v19, 0xffff0000, v32
	v_mul_f32_e32 v0, v3, v3
	v_lshlrev_b32_e32 v32, 16, v33
	v_fmac_f32_e32 v0, v19, v19
	v_and_b32_e32 v33, 0xffff0000, v33
	v_fmac_f32_e32 v0, v32, v32
	v_lshlrev_b32_e32 v36, 16, v34
	v_fmac_f32_e32 v0, v33, v33
	v_and_b32_e32 v34, 0xffff0000, v34
	v_fmac_f32_e32 v0, v36, v36
	v_lshlrev_b32_e32 v37, 16, v35
	v_fmac_f32_e32 v0, v34, v34
	v_and_b32_e32 v35, 0xffff0000, v35
	v_fmac_f32_e32 v0, v37, v37
	v_fmac_f32_e32 v0, v35, v35
	s_waitcnt lgkmcnt(0)
	s_nop 1
	v_add_f32_dpp v0, v0, v0 quad_perm:[1,0,3,2] row_mask:0xf bank_mask:0xf
	s_waitcnt lgkmcnt(0)
	s_nop 1
	v_add_f32_dpp v0, v0, v0 quad_perm:[2,3,0,1] row_mask:0xf bank_mask:0xf
	s_waitcnt lgkmcnt(0)
	s_nop 1
	v_add_f32_dpp v0, v0, v0 row_half_mirror row_mask:0xf bank_mask:0xf
	s_waitcnt lgkmcnt(0)
	s_nop 1
	v_add_f32_dpp v0, v0, v0 row_mirror row_mask:0xf bank_mask:0xf
	ds_swizzle_b32 v2, v0 offset:swizzle(SWAP,16)
	s_waitcnt vmcnt(2)
	v_lshlrev_b32_e32 v39, 16, v21
	v_and_b32_e32 v21, 0xffff0000, v21
	v_lshlrev_b32_e32 v40, 16, v22
	v_and_b32_e32 v22, 0xffff0000, v22
	v_lshlrev_b32_e32 v41, 16, v23
	v_and_b32_e32 v23, 0xffff0000, v23
	v_lshlrev_b32_e32 v38, 16, v20
	v_and_b32_e32 v20, 0xffff0000, v20
	v_mul_f32_e32 v21, v21, v33
	v_mul_f32_e32 v22, v22, v34
	v_mul_f32_e32 v23, v23, v35
	v_mul_f32_e32 v3, v38, v3
	v_mul_f32_e32 v19, v20, v19
	v_mul_f32_e32 v20, v39, v32
	v_mul_f32_e32 v32, v40, v36
	v_mul_f32_e32 v33, v41, v37
	s_waitcnt vmcnt(1)
	v_mul_f32_e32 v21, v27, v21
	s_waitcnt vmcnt(0)
	v_mul_f32_e32 v22, v29, v22
	v_mul_f32_e32 v23, v31, v23
	v_mul_f32_e32 v3, v24, v3
	v_mul_f32_e32 v19, v25, v19
	v_mul_f32_e32 v24, v26, v20
	v_mul_f32_e32 v25, v28, v32
	v_mul_f32_e32 v26, v30, v33
	v_cvt_pk_bf16_f32 v20, v3, v19
	v_cvt_pk_bf16_f32 v21, v24, v21
	v_cvt_pk_bf16_f32 v22, v25, v22
	v_cvt_pk_bf16_f32 v23, v26, v23
	global_store_dwordx4 v[16:17], v[20:23], off
	s_and_saveexec_b64 s[10:11], s[4:5]
	s_cbranch_execz .LBB0_386
	v_add_co_u32_e32 v14, vcc, 0x16201000, v14
	s_waitcnt lgkmcnt(0)
	v_add_f32_e32 v0, v0, v2
	v_addc_co_u32_e32 v15, vcc, 0, v15, vcc
	v_mov_b32_e32 v2, v1
	v_mov_b32_e32 v3, v1
	global_store_dwordx4 v[14:15], v[0:3], off offset:2048
	s_branch .LBB0_386

; __device__ __forceinline__ unsigned cvtpk(float lo, float hi) { unsigned r; asm("v_cvt_pk_bf16_f32 %0, %1, %2" : "=v"(r) : "v"(lo), "v"(hi)); return r; }
; __device__ __forceinline__ float red32(float v) { v += sxor<1>(v); v += sxor<2>(v); v += sxor<4>(v); v += sxor<8>(v); v += sxor<16>(v); return v; }
; __device__ __forceinline__ float blo(unsigned w) { return __uint_as_float(w << 16); }
; __device__ __forceinline__ float bhi(unsigned w) { return __uint_as_float(w & 0xffff0000u); }
; template <int kind> __device__ __forceinline__ void gemm_phase_n(const Params& P, int layer, int b, const int wv) {
;     ...
;                 DRAIN_BEGIN const size_t t = pm * 256 + row; const size_t idx = t * 1024 + pn * 256 + chunk * 8;
;                     const u32x4 pw = *(const u32x4*)(pscr + (size_t)row * 256 + chunk * 8); const u32x4 xw = *(const u32x4*)(x1b + idx);
;                     f32x4 xa = f32x4{blo(xw[0]), bhi(xw[0]), blo(xw[1]), bhi(xw[1])}, xc = f32x4{blo(xw[2]), bhi(xw[2]), blo(xw[3]), bhi(xw[3])};
;                     xa[0] += blo(pw[0]) * blo(w[0]); xa[1] += bhi(pw[0]) * bhi(w[0]); xa[2] += blo(pw[1]) * blo(w[1]); xa[3] += bhi(pw[1]) * bhi(w[1]);
;                     xc[0] += blo(pw[2]) * blo(w[2]); xc[1] += bhi(pw[2]) * bhi(w[2]); xc[2] += blo(pw[3]) * blo(w[3]); xc[3] += bhi(pw[3]) * bhi(w[3]);
;                     if (layer == 3) { *(f32x4*)(out + idx) = xa; *(f32x4*)(out + idx + 4) = xc; }
;                     *(u32x4*)(xb + idx) = u32x4{cvtpk(xa[0], xa[1]), cvtpk(xa[2], xa[3]), cvtpk(xc[0], xc[1]), cvtpk(xc[2], xc[3])};
;                     float ss = xa[0] * xa[0] + xa[1] * xa[1] + xa[2] * xa[2] + xa[3] * xa[3] + xc[0] * xc[0] + xc[1] * xc[1] + xc[2] * xc[2] + xc[3] * xc[3];
;                     ss = red32(ss); if (chunk == 0) *(f32x4*)(rowss + t * 16 + pn * 4) = f32x4{ss, 0.f, 0.f, 0.f};
.LBB0_641:
	v_lshl_add_u64 v[150:151], v[142:143], 0, s[8:9]
	v_add_co_u32_e32 v2, vcc, 0x17880000, v150
	ds_read_b128 v[136:139], v167
	s_nop 0
	v_addc_co_u32_e32 v3, vcc, 0, v151, vcc
	global_load_dwordx4 v[168:171], v[2:3], off
	v_lshl_add_u64 v[2:3], v[146:147], 0, s[8:9]
	s_waitcnt lgkmcnt(1)
	v_add_co_u32_e32 v132, vcc, s85, v2
	s_waitcnt lgkmcnt(0)
	v_lshlrev_b32_e32 v152, 16, v136
	v_addc_co_u32_e32 v133, vcc, 0, v3, vcc
	global_load_dwordx4 v[172:175], v[132:133], off
	v_add_u32_e32 v96, s30, v166
	v_add_u32_e32 v98, 16, v96
	v_ashrrev_i32_e32 v99, 31, v98
	v_lshlrev_b64 v[90:91], 10, v[98:99]
	v_lshl_add_u64 v[90:91], v[90:91], 0, v[140:141]
	v_add_co_u32_e32 v94, vcc, 0x17882000, v150
	s_nop 1
	v_addc_co_u32_e32 v95, vcc, 0, v151, vcc
	global_load_dwordx4 v[66:69], v[94:95], off
	v_lshl_add_u64 v[92:93], v[90:91], 1, s[10:11]
	global_load_dwordx4 v[70:73], v[92:93], off
	v_add_u32_e32 v98, 32, v96
	v_ashrrev_i32_e32 v99, 31, v98
	v_lshlrev_b64 v[90:91], 10, v[98:99]
	v_lshl_add_u64 v[90:91], v[90:91], 0, v[140:141]
	v_add_co_u32_e32 v94, vcc, 0x17884000, v150
	s_nop 1
	v_addc_co_u32_e32 v95, vcc, 0, v151, vcc
	global_load_dwordx4 v[74:77], v[94:95], off
	v_lshl_add_u64 v[92:93], v[90:91], 1, s[10:11]
	global_load_dwordx4 v[78:81], v[92:93], off
	v_add_u32_e32 v98, 48, v96
	v_ashrrev_i32_e32 v99, 31, v98
	v_lshlrev_b64 v[90:91], 10, v[98:99]
	v_lshl_add_u64 v[90:91], v[90:91], 0, v[140:141]
	v_add_co_u32_e32 v94, vcc, 0x17886000, v150
	s_nop 1
	v_addc_co_u32_e32 v95, vcc, 0, v151, vcc
	global_load_dwordx4 v[82:85], v[94:95], off
	v_lshl_add_u64 v[92:93], v[90:91], 1, s[10:11]
	global_load_dwordx4 v[86:89], v[92:93], off
	v_and_b32_e32 v153, 0xffff0000, v136
	v_lshlrev_b32_e32 v136, 16, v137
	v_and_b32_e32 v137, 0xffff0000, v137
	v_cndmask_b32_e64 v0, 0, 1, s[92:93]
	v_cmp_ne_u32_e64 s[6:7], 1, v0
	s_andn2_b64 vcc, exec, s[92:93]
	s_waitcnt vmcnt(7)
	v_lshlrev_b32_e32 v134, 16, v168
	v_and_b32_e32 v135, 0xffff0000, v168
	v_lshlrev_b32_e32 v168, 16, v138
	s_waitcnt vmcnt(6)
	v_lshlrev_b32_e32 v132, 16, v172
	v_and_b32_e32 v133, 0xffff0000, v172
	v_pk_fma_f32 v[132:133], v[152:153], v[134:135], v[132:133]
	v_lshlrev_b32_e32 v134, 16, v173
	v_and_b32_e32 v135, 0xffff0000, v173
	v_lshlrev_b32_e32 v152, 16, v169
	v_and_b32_e32 v153, 0xffff0000, v169
	v_pk_fma_f32 v[134:135], v[136:137], v[152:153], v[134:135]
	v_lshlrev_b32_e32 v136, 16, v174
	v_and_b32_e32 v137, 0xffff0000, v174
	v_lshlrev_b32_e32 v152, 16, v170
	v_and_b32_e32 v153, 0xffff0000, v170
	v_and_b32_e32 v169, 0xffff0000, v138
	v_pk_fma_f32 v[136:137], v[168:169], v[152:153], v[136:137]
	v_lshlrev_b32_e32 v152, 16, v175
	v_and_b32_e32 v153, 0xffff0000, v175
	v_lshlrev_b32_e32 v168, 16, v171
	v_and_b32_e32 v169, 0xffff0000, v171
	v_lshlrev_b32_e32 v138, 16, v139
	v_and_b32_e32 v139, 0xffff0000, v139
	v_pk_fma_f32 v[138:139], v[138:139], v[168:169], v[152:153]
	s_cbranch_vccnz .LBB0_643
	global_store_dwordx4 v[148:149], v[132:135], off offset:-16
	global_store_dwordx4 v[148:149], v[136:139], off
.LBB0_643:
	v_add_co_u32_e32 v2, vcc, 0x4c00000, v2
	v_cvt_pk_bf16_f32 v168, v132, v133
	v_cvt_pk_bf16_f32 v169, v134, v135
	v_cvt_pk_bf16_f32 v170, v136, v137
	v_cvt_pk_bf16_f32 v171, v138, v139
	s_nop 1
	v_addc_co_u32_e32 v3, vcc, 0, v3, vcc
	global_store_dwordx4 v[2:3], v[168:171], off
	v_pk_mul_f32 v[2:3], v[132:133], v[132:133]
	v_pk_mul_f32 v[132:133], v[134:135], v[134:135]
	v_add_f32_e32 v0, v2, v3
	v_add_f32_e32 v0, v132, v0
	v_pk_mul_f32 v[134:135], v[136:137], v[136:137]
	v_add_f32_e32 v0, v133, v0
	v_add_f32_e32 v0, v134, v0
	v_pk_mul_f32 v[136:137], v[138:139], v[138:139]
	v_add_f32_e32 v0, v135, v0
	v_add_f32_e32 v0, v136, v0
	v_add_f32_e32 v0, v137, v0
	s_waitcnt lgkmcnt(0)
	s_nop 1
	v_add_f32_dpp v0, v0, v0 quad_perm:[1,0,3,2] row_mask:0xf bank_mask:0xf
	s_waitcnt lgkmcnt(0)
	s_nop 1
	v_add_f32_dpp v0, v0, v0 quad_perm:[2,3,0,1] row_mask:0xf bank_mask:0xf
	s_waitcnt lgkmcnt(0)
	s_nop 1
	v_add_f32_dpp v0, v0, v0 row_half_mirror row_mask:0xf bank_mask:0xf
	s_waitcnt lgkmcnt(0)
	s_nop 1
	v_add_f32_dpp v0, v0, v0 row_mirror row_mask:0xf bank_mask:0xf
	ds_swizzle_b32 v2, v0 offset:swizzle(SWAP,16)
	s_and_saveexec_b64 s[28:29], s[4:5]
	s_cbranch_execz .LBB0_645
	v_lshl_add_u64 v[132:133], v[144:145], 0, s[8:9]
	s_waitcnt lgkmcnt(0)
	v_add_f32_e32 v0, v0, v2
	v_mov_b32_e32 v2, v1
	v_mov_b32_e32 v3, v1
	global_store_dwordx4 v[132:133], v[0:3], off
; __device__ __forceinline__ unsigned cvtpk(float lo, float hi) { unsigned r; asm("v_cvt_pk_bf16_f32 %0, %1, %2" : "=v"(r) : "v"(lo), "v"(hi)); return r; }
; __device__ __forceinline__ float red32(float v) { v += sxor<1>(v); v += sxor<2>(v); v += sxor<4>(v); v += sxor<8>(v); v += sxor<16>(v); return v; }
; __device__ __forceinline__ float blo(unsigned w) { return __uint_as_float(w << 16); }
; __device__ __forceinline__ float bhi(unsigned w) { return __uint_as_float(w & 0xffff0000u); }
; template <int kind> __device__ __forceinline__ void gemm_phase_n(const Params& P, int layer, int b, const int wv) {
;     ...
;                 DRAIN_BEGIN const size_t t = pm * 256 + row; const size_t idx = t * 1024 + pn * 256 + chunk * 8;
;                     const u32x4 pw = *(const u32x4*)(pscr + (size_t)row * 256 + chunk * 8); const u32x4 xw = *(const u32x4*)(x1b + idx);
;                     f32x4 xa = f32x4{blo(xw[0]), bhi(xw[0]), blo(xw[1]), bhi(xw[1])}, xc = f32x4{blo(xw[2]), bhi(xw[2]), blo(xw[3]), bhi(xw[3])};
;                     xa[0] += blo(pw[0]) * blo(w[0]); xa[1] += bhi(pw[0]) * bhi(w[0]); xa[2] += blo(pw[1]) * blo(w[1]); xa[3] += bhi(pw[1]) * bhi(w[1]);
;                     xc[0] += blo(pw[2]) * blo(w[2]); xc[1] += bhi(pw[2]) * bhi(w[2]); xc[2] += blo(pw[3]) * blo(w[3]); xc[3] += bhi(pw[3]) * bhi(w[3]);
;                     if (layer == 3) { *(f32x4*)(out + idx) = xa; *(f32x4*)(out + idx + 4) = xc; }
;                     *(u32x4*)(xb + idx) = u32x4{cvtpk(xa[0], xa[1]), cvtpk(xa[2], xa[3]), cvtpk(xc[0], xc[1]), cvtpk(xc[2], xc[3])};
;                     float ss = xa[0] * xa[0] + xa[1] * xa[1] + xa[2] * xa[2] + xa[3] * xa[3] + xc[0] * xc[0] + xc[1] * xc[1] + xc[2] * xc[2] + xc[3] * xc[3];
;                     ss = red32(ss); if (chunk == 0) *(f32x4*)(rowss + t * 16 + pn * 4) = f32x4{ss, 0.f, 0.f, 0.f};
.LBB0_645:
	s_or_b64 exec, exec, s[28:29]
	v_add_u32_e32 v168, s30, v166
	s_waitcnt lgkmcnt(0)
	v_add_u32_e32 v2, 16, v168
	v_ashrrev_i32_e32 v3, 31, v2
	v_lshlrev_b64 v[132:133], 10, v[2:3]
	v_lshl_add_u64 v[152:153], v[132:133], 0, v[140:141]
	v_add_co_u32_e32 v132, vcc, 0x17882000, v150
	ds_read_b128 v[136:139], v167 offset:8704
	s_nop 0
	v_addc_co_u32_e32 v133, vcc, 0, v151, vcc
	v_lshl_add_u64 v[132:133], v[152:153], 1, s[10:11]
	s_waitcnt lgkmcnt(0)
	v_lshlrev_b32_e32 v178, 16, v136
	v_and_b32_e32 v179, 0xffff0000, v136
	v_lshlrev_b32_e32 v136, 16, v137
	v_and_b32_e32 v137, 0xffff0000, v137
	s_and_b64 vcc, exec, s[6:7]
	s_waitcnt vmcnt(6)
	v_mov_b32_e32 v170, v66
	v_mov_b32_e32 v171, v67
	v_mov_b32_e32 v172, v68
	v_mov_b32_e32 v173, v69
	v_lshlrev_b32_e32 v134, 16, v170
	v_and_b32_e32 v135, 0xffff0000, v170
	v_mov_b32_e32 v174, v70
	v_mov_b32_e32 v175, v71
	v_mov_b32_e32 v176, v72
	v_mov_b32_e32 v177, v73
	v_lshlrev_b32_e32 v132, 16, v174
	v_and_b32_e32 v133, 0xffff0000, v174
	v_pk_fma_f32 v[132:133], v[178:179], v[134:135], v[132:133]
	v_lshlrev_b32_e32 v134, 16, v175
	v_and_b32_e32 v135, 0xffff0000, v175
	v_lshlrev_b32_e32 v170, 16, v171
	v_and_b32_e32 v171, 0xffff0000, v171
	v_pk_fma_f32 v[134:135], v[136:137], v[170:171], v[134:135]
	v_lshlrev_b32_e32 v136, 16, v176
	v_and_b32_e32 v137, 0xffff0000, v176
	v_lshlrev_b32_e32 v170, 16, v172
	v_and_b32_e32 v171, 0xffff0000, v172
	v_lshlrev_b32_e32 v174, 16, v138
	v_and_b32_e32 v175, 0xffff0000, v138
	v_pk_fma_f32 v[136:137], v[174:175], v[170:171], v[136:137]
	v_lshlrev_b32_e32 v170, 16, v177
	v_and_b32_e32 v171, 0xffff0000, v177
	v_lshlrev_b32_e32 v172, 16, v173
	v_and_b32_e32 v173, 0xffff0000, v173
	v_lshlrev_b32_e32 v138, 16, v139
	v_and_b32_e32 v139, 0xffff0000, v139
	v_pk_fma_f32 v[138:139], v[138:139], v[172:173], v[170:171]
	s_cbranch_vccnz .LBB0_647
	v_lshl_add_u64 v[170:171], v[152:153], 2, s[86:87]
	global_store_dwordx4 v[170:171], v[132:135], off
	global_store_dwordx4 v[170:171], v[136:139], off offset:16
.LBB0_647:
	v_cvt_pk_bf16_f32 v170, v132, v133
	s_nop 0
	v_pk_mul_f32 v[132:133], v[132:133], v[132:133]
	v_cvt_pk_bf16_f32 v171, v134, v135
	v_pk_mul_f32 v[134:135], v[134:135], v[134:135]
	v_add_f32_e32 v0, v132, v133
	v_add_f32_e32 v0, v134, v0
	v_cvt_pk_bf16_f32 v172, v136, v137
	v_pk_mul_f32 v[136:137], v[136:137], v[136:137]
	v_add_f32_e32 v0, v135, v0
	v_add_f32_e32 v0, v136, v0
	v_cvt_pk_bf16_f32 v173, v138, v139
	v_pk_mul_f32 v[138:139], v[138:139], v[138:139]
	v_add_f32_e32 v0, v137, v0
	v_add_f32_e32 v0, v138, v0
	v_add_f32_e32 v0, v139, v0
	ds_swizzle_b32 v132, v0 offset:swizzle(SWAP,1)
	v_lshl_add_u64 v[152:153], v[152:153], 1, s[12:13]
	global_store_dwordx4 v[152:153], v[170:173], off
	s_waitcnt lgkmcnt(0)
	v_add_f32_e32 v0, v0, v132
	s_waitcnt lgkmcnt(0)
	s_nop 1
	v_add_f32_dpp v0, v0, v0 quad_perm:[2,3,0,1] row_mask:0xf bank_mask:0xf
	s_waitcnt lgkmcnt(0)
	s_nop 1
	v_add_f32_dpp v0, v0, v0 row_half_mirror row_mask:0xf bank_mask:0xf
	s_waitcnt lgkmcnt(0)
	s_nop 1
	v_add_f32_dpp v0, v0, v0 row_mirror row_mask:0xf bank_mask:0xf
	ds_swizzle_b32 v132, v0 offset:swizzle(SWAP,16)
	s_and_saveexec_b64 s[28:29], s[4:5]
	s_cbranch_execz .LBB0_649
	v_lshlrev_b64 v[2:3], 6, v[2:3]
	v_lshl_add_u64 v[134:135], s[24:25], 0, v[2:3]
	s_waitcnt lgkmcnt(0)
	v_add_f32_e32 v0, v0, v132
	v_mov_b32_e32 v2, v1
	v_mov_b32_e32 v3, v1
	global_store_dwordx4 v[134:135], v[0:3], off
.LBB0_649:
	s_or_b64 exec, exec, s[28:29]
	s_nop 0
	v_add_u32_e32 v2, 32, v168
	v_ashrrev_i32_e32 v3, 31, v2
	s_waitcnt lgkmcnt(0)
	v_lshlrev_b64 v[132:133], 10, v[2:3]
	v_lshl_add_u64 v[152:153], v[132:133], 0, v[140:141]
	v_add_co_u32_e32 v132, vcc, 0x17884000, v150
	ds_read_b128 v[136:139], v167 offset:17408
	s_nop 0
	v_addc_co_u32_e32 v133, vcc, 0, v151, vcc
	v_lshl_add_u64 v[132:133], v[152:153], 1, s[10:11]
	s_waitcnt lgkmcnt(0)
	v_lshlrev_b32_e32 v178, 16, v136
	v_and_b32_e32 v179, 0xffff0000, v136
	v_lshlrev_b32_e32 v136, 16, v137
	v_and_b32_e32 v137, 0xffff0000, v137
	s_and_b64 vcc, exec, s[6:7]
	s_waitcnt vmcnt(6)
	v_mov_b32_e32 v170, v74
	v_mov_b32_e32 v171, v75
	v_mov_b32_e32 v172, v76
	v_mov_b32_e32 v173, v77
	v_lshlrev_b32_e32 v134, 16, v170
	v_and_b32_e32 v135, 0xffff0000, v170
	v_mov_b32_e32 v174, v78
	v_mov_b32_e32 v175, v79
	v_mov_b32_e32 v176, v80
	v_mov_b32_e32 v177, v81
	v_lshlrev_b32_e32 v132, 16, v174
	v_and_b32_e32 v133, 0xffff0000, v174
	v_pk_fma_f32 v[132:133], v[178:179], v[134:135], v[132:133]
	v_lshlrev_b32_e32 v134, 16, v175
	v_and_b32_e32 v135, 0xffff0000, v175
	v_lshlrev_b32_e32 v170, 16, v171
	v_and_b32_e32 v171, 0xffff0000, v171
	v_pk_fma_f32 v[134:135], v[136:137], v[170:171], v[134:135]
	v_lshlrev_b32_e32 v136, 16, v176
	v_and_b32_e32 v137, 0xffff0000, v176
	v_lshlrev_b32_e32 v170, 16, v172
	v_and_b32_e32 v171, 0xffff0000, v172
	v_lshlrev_b32_e32 v174, 16, v138
	v_and_b32_e32 v175, 0xffff0000, v138
	v_pk_fma_f32 v[136:137], v[174:175], v[170:171], v[136:137]
	v_lshlrev_b32_e32 v170, 16, v177
	v_and_b32_e32 v171, 0xffff0000, v177
	v_lshlrev_b32_e32 v172, 16, v173
	v_and_b32_e32 v173, 0xffff0000, v173
	v_lshlrev_b32_e32 v138, 16, v139
	v_and_b32_e32 v139, 0xffff0000, v139
	v_pk_fma_f32 v[138:139], v[138:139], v[172:173], v[170:171]
	s_cbranch_vccnz .LBB0_651
	v_lshl_add_u64 v[170:171], v[152:153], 2, s[86:87]
	global_store_dwordx4 v[170:171], v[132:135], off
	global_store_dwordx4 v[170:171], v[136:139], off offset:16

; __device__ __forceinline__ unsigned cvtpk(float lo, float hi) { unsigned r; asm("v_cvt_pk_bf16_f32 %0, %1, %2" : "=v"(r) : "v"(lo), "v"(hi)); return r; }
; __device__ __forceinline__ float red32(float v) { v += sxor<1>(v); v += sxor<2>(v); v += sxor<4>(v); v += sxor<8>(v); v += sxor<16>(v); return v; }
; __device__ __forceinline__ float blo(unsigned w) { return __uint_as_float(w << 16); }
; __device__ __forceinline__ float bhi(unsigned w) { return __uint_as_float(w & 0xffff0000u); }
; template <int kind> __device__ __forceinline__ void gemm_phase_n(const Params& P, int layer, int b, const int wv) {
;     ...
;                 DRAIN_BEGIN const size_t t = pm * 256 + row; const size_t idx = t * 1024 + pn * 256 + chunk * 8;
;                     const u32x4 pw = *(const u32x4*)(pscr + (size_t)row * 256 + chunk * 8); const u32x4 xw = *(const u32x4*)(x1b + idx);
;                     f32x4 xa = f32x4{blo(xw[0]), bhi(xw[0]), blo(xw[1]), bhi(xw[1])}, xc = f32x4{blo(xw[2]), bhi(xw[2]), blo(xw[3]), bhi(xw[3])};
;                     xa[0] += blo(pw[0]) * blo(w[0]); xa[1] += bhi(pw[0]) * bhi(w[0]); xa[2] += blo(pw[1]) * blo(w[1]); xa[3] += bhi(pw[1]) * bhi(w[1]);
;                     xc[0] += blo(pw[2]) * blo(w[2]); xc[1] += bhi(pw[2]) * bhi(w[2]); xc[2] += blo(pw[3]) * blo(w[3]); xc[3] += bhi(pw[3]) * bhi(w[3]);
;                     if (layer == 3) { *(f32x4*)(out + idx) = xa; *(f32x4*)(out + idx + 4) = xc; }
;                     *(u32x4*)(xb + idx) = u32x4{cvtpk(xa[0], xa[1]), cvtpk(xa[2], xa[3]), cvtpk(xc[0], xc[1]), cvtpk(xc[2], xc[3])};
;                     float ss = xa[0] * xa[0] + xa[1] * xa[1] + xa[2] * xa[2] + xa[3] * xa[3] + xc[0] * xc[0] + xc[1] * xc[1] + xc[2] * xc[2] + xc[3] * xc[3];
;                     ss = red32(ss); if (chunk == 0) *(f32x4*)(rowss + t * 16 + pn * 4) = f32x4{ss, 0.f, 0.f, 0.f};
.LBB0_653:
	s_or_b64 exec, exec, s[28:29]
	s_nop 0
	v_add_u32_e32 v2, 48, v168
	v_ashrrev_i32_e32 v3, 31, v2
	s_waitcnt lgkmcnt(0)
	v_lshlrev_b64 v[132:133], 10, v[2:3]
	v_lshl_add_u64 v[152:153], v[132:133], 0, v[140:141]
	v_add_co_u32_e32 v132, vcc, 0x17886000, v150
	ds_read_b128 v[136:139], v167 offset:26112
	s_nop 0
	v_addc_co_u32_e32 v133, vcc, 0, v151, vcc
	v_lshl_add_u64 v[132:133], v[152:153], 1, s[10:11]
	s_waitcnt lgkmcnt(0)
	v_lshlrev_b32_e32 v150, 16, v136
	v_and_b32_e32 v151, 0xffff0000, v136
	v_lshlrev_b32_e32 v136, 16, v137
	v_and_b32_e32 v137, 0xffff0000, v137
	s_and_b64 vcc, exec, s[6:7]
	s_waitcnt vmcnt(6)
	v_mov_b32_e32 v168, v82
	v_mov_b32_e32 v169, v83
	v_mov_b32_e32 v170, v84
	v_mov_b32_e32 v171, v85
	v_lshlrev_b32_e32 v134, 16, v168
	v_and_b32_e32 v135, 0xffff0000, v168
	v_mov_b32_e32 v172, v86
	v_mov_b32_e32 v173, v87
	v_mov_b32_e32 v174, v88
	v_mov_b32_e32 v175, v89
	v_lshlrev_b32_e32 v132, 16, v172
	v_and_b32_e32 v133, 0xffff0000, v172
	v_pk_fma_f32 v[132:133], v[150:151], v[134:135], v[132:133]
	v_lshlrev_b32_e32 v134, 16, v173
	v_and_b32_e32 v135, 0xffff0000, v173
	v_lshlrev_b32_e32 v150, 16, v169
	v_and_b32_e32 v151, 0xffff0000, v169
	v_pk_fma_f32 v[134:135], v[136:137], v[150:151], v[134:135]
	v_lshlrev_b32_e32 v136, 16, v174
	v_and_b32_e32 v137, 0xffff0000, v174
	v_lshlrev_b32_e32 v150, 16, v170
	v_and_b32_e32 v151, 0xffff0000, v170
	v_lshlrev_b32_e32 v168, 16, v138
	v_and_b32_e32 v169, 0xffff0000, v138
	v_pk_fma_f32 v[136:137], v[168:169], v[150:151], v[136:137]
	v_lshlrev_b32_e32 v150, 16, v175
	v_and_b32_e32 v151, 0xffff0000, v175
	v_lshlrev_b32_e32 v168, 16, v171
	v_and_b32_e32 v169, 0xffff0000, v171
	v_lshlrev_b32_e32 v138, 16, v139
	v_and_b32_e32 v139, 0xffff0000, v139
	v_pk_fma_f32 v[138:139], v[138:139], v[168:169], v[150:151]
	s_cbranch_vccnz .LBB0_655
	v_lshl_add_u64 v[150:151], v[152:153], 2, s[86:87]
	global_store_dwordx4 v[150:151], v[132:135], off
	global_store_dwordx4 v[150:151], v[136:139], off offset:16
.LBB0_655:
	v_cvt_pk_bf16_f32 v168, v132, v133
	s_nop 0
	v_pk_mul_f32 v[132:133], v[132:133], v[132:133]
	v_cvt_pk_bf16_f32 v169, v134, v135
	v_pk_mul_f32 v[134:135], v[134:135], v[134:135]
	v_add_f32_e32 v0, v132, v133
	v_add_f32_e32 v0, v134, v0
	v_cvt_pk_bf16_f32 v170, v136, v137
	v_pk_mul_f32 v[136:137], v[136:137], v[136:137]
	v_add_f32_e32 v0, v135, v0
	v_add_f32_e32 v0, v136, v0
	v_cvt_pk_bf16_f32 v171, v138, v139
	v_pk_mul_f32 v[138:139], v[138:139], v[138:139]
	v_add_f32_e32 v0, v137, v0
	v_add_f32_e32 v0, v138, v0
	v_add_f32_e32 v0, v139, v0
	ds_swizzle_b32 v132, v0 offset:swizzle(SWAP,1)
	v_lshl_add_u64 v[150:151], v[152:153], 1, s[12:13]
	global_store_dwordx4 v[150:151], v[168:171], off
	s_waitcnt lgkmcnt(0)
	v_add_f32_e32 v0, v0, v132
	s_waitcnt lgkmcnt(0)
	s_nop 1
	v_add_f32_dpp v0, v0, v0 quad_perm:[2,3,0,1] row_mask:0xf bank_mask:0xf
	s_waitcnt lgkmcnt(0)
	s_nop 1
	v_add_f32_dpp v0, v0, v0 row_half_mirror row_mask:0xf bank_mask:0xf
	s_waitcnt lgkmcnt(0)
	s_nop 1
	v_add_f32_dpp v0, v0, v0 row_mirror row_mask:0xf bank_mask:0xf
	ds_swizzle_b32 v132, v0 offset:swizzle(SWAP,16)
	s_and_saveexec_b64 s[6:7], s[4:5]
	s_cbranch_execz .LBB0_640
	v_lshlrev_b64 v[2:3], 6, v[2:3]
	v_lshl_add_u64 v[134:135], s[24:25], 0, v[2:3]
	s_waitcnt lgkmcnt(0)
	v_add_f32_e32 v0, v0, v132
	v_mov_b32_e32 v2, v1
	v_mov_b32_e32 v3, v1
	global_store_dwordx4 v[134:135], v[0:3], off
	s_branch .LBB0_640

; __device__ __forceinline__ float red32(float v) { v += sxor<1>(v); v += sxor<2>(v); v += sxor<4>(v); v += sxor<8>(v); v += sxor<16>(v); return v; }
; __device__ __forceinline__ float blo(unsigned w) { return __uint_as_float(w << 16); }
; __device__ __forceinline__ float bhi(unsigned w) { return __uint_as_float(w & 0xffff0000u); }
; template <int kind> __device__ __forceinline__ void gemm_phase_n(const Params& P, int layer, int b, const int wv) {
;     ...
;                     DRAIN_BEGIN *(u32x4*)(dst + (size_t)row * ldd + chunk * 8) = w;
;                         const float o0 = blo(w[0]), o1 = bhi(w[0]), o2 = blo(w[1]), o3 = bhi(w[1]), o4 = blo(w[2]), o5 = bhi(w[2]), o6 = blo(w[3]), o7 = bhi(w[3]);
;                         float ss = o0 * o0 + o1 * o1 + o2 * o2 + o3 * o3 + o4 * o4 + o5 * o5 + o6 * o6 + o7 * o7;
;                         ss = red32(ss); if (chunk == 0) *(f32x4*)(ssp + (size_t)row * sst) = f32x4{ss, 0.f, 0.f, 0.f};
;                     LOOP_END
.LBB0_694:
	ds_read_b128 v[20:23], v18
	s_waitcnt lgkmcnt(1)
	v_lshl_add_u64 v[2:3], v[6:7], 0, v[14:15]
	v_lshl_add_u64 v[16:17], v[4:5], 0, s[10:11]
	s_waitcnt lgkmcnt(0)
	global_store_dwordx4 v[2:3], v[20:23], off
	v_and_b32_e32 v2, 0xffff0000, v20
	v_lshlrev_b32_e32 v0, 16, v20
	v_mul_f32_e32 v2, v2, v2
	v_lshlrev_b32_e32 v3, 16, v21
	v_fmac_f32_e32 v2, v0, v0
	v_and_b32_e32 v19, 0xffff0000, v21
	v_fmac_f32_e32 v2, v3, v3
	v_lshlrev_b32_e32 v20, 16, v22
	v_fmac_f32_e32 v2, v19, v19
	v_and_b32_e32 v21, 0xffff0000, v22
	v_fmac_f32_e32 v2, v20, v20
	v_lshlrev_b32_e32 v22, 16, v23
	v_fmac_f32_e32 v2, v21, v21
	v_and_b32_e32 v23, 0xffff0000, v23
	v_fmac_f32_e32 v2, v22, v22
	v_fmac_f32_e32 v2, v23, v23
	s_waitcnt lgkmcnt(0)
	s_nop 1
	v_add_f32_dpp v0, v2, v2 quad_perm:[1,0,3,2] row_mask:0xf bank_mask:0xf
	s_waitcnt lgkmcnt(0)
	s_nop 1
	v_add_f32_dpp v0, v0, v0 quad_perm:[2,3,0,1] row_mask:0xf bank_mask:0xf
	s_waitcnt lgkmcnt(0)
	s_nop 1
	v_add_f32_dpp v0, v0, v0 row_half_mirror row_mask:0xf bank_mask:0xf
	s_waitcnt lgkmcnt(0)
	s_nop 1
	v_add_f32_dpp v0, v0, v0 row_mirror row_mask:0xf bank_mask:0xf
	ds_swizzle_b32 v2, v0 offset:swizzle(SWAP,16)
	s_and_saveexec_b64 s[14:15], vcc
	s_cbranch_execz .LBB0_696
	v_lshlrev_b64 v[20:21], s12, v[16:17]
	v_lshl_add_u64 v[20:21], v[20:21], 2, s[2:3]
	s_waitcnt lgkmcnt(0)
	v_add_f32_e32 v0, v0, v2
	v_mov_b32_e32 v2, v1
	v_mov_b32_e32 v3, v1
	global_store_dwordx4 v[20:21], v[0:3], off
.LBB0_696:
	s_or_b64 exec, exec, s[14:15]
	ds_read_b128 v[20:23], v18 offset:8704
	s_waitcnt lgkmcnt(1)
	v_lshl_add_u64 v[2:3], v[6:7], 0, v[12:13]
	s_waitcnt lgkmcnt(0)
	global_store_dwordx4 v[2:3], v[20:23], off
	v_and_b32_e32 v2, 0xffff0000, v20
	v_lshlrev_b32_e32 v0, 16, v20
	v_mul_f32_e32 v2, v2, v2
	v_lshlrev_b32_e32 v3, 16, v21
	v_fmac_f32_e32 v2, v0, v0
	v_and_b32_e32 v19, 0xffff0000, v21
	v_fmac_f32_e32 v2, v3, v3
	v_lshlrev_b32_e32 v20, 16, v22
	v_fmac_f32_e32 v2, v19, v19
	v_and_b32_e32 v21, 0xffff0000, v22
	v_fmac_f32_e32 v2, v20, v20
	v_lshlrev_b32_e32 v22, 16, v23
	v_fmac_f32_e32 v2, v21, v21
	v_and_b32_e32 v23, 0xffff0000, v23
	v_fmac_f32_e32 v2, v22, v22
	v_fmac_f32_e32 v2, v23, v23
	s_waitcnt lgkmcnt(0)
	s_nop 1
	v_add_f32_dpp v0, v2, v2 quad_perm:[1,0,3,2] row_mask:0xf bank_mask:0xf
	s_waitcnt lgkmcnt(0)
	s_nop 1
	v_add_f32_dpp v0, v0, v0 quad_perm:[2,3,0,1] row_mask:0xf bank_mask:0xf
	s_waitcnt lgkmcnt(0)
	s_nop 1
	v_add_f32_dpp v0, v0, v0 row_half_mirror row_mask:0xf bank_mask:0xf
	s_waitcnt lgkmcnt(0)
	s_nop 1
	v_add_f32_dpp v0, v0, v0 row_mirror row_mask:0xf bank_mask:0xf
	ds_swizzle_b32 v2, v0 offset:swizzle(SWAP,16)
	s_and_saveexec_b64 s[14:15], vcc
	s_cbranch_execz .LBB0_698
	v_lshl_add_u64 v[20:21], v[16:17], 0, 16
	v_lshlrev_b64 v[20:21], s12, v[20:21]
	v_lshl_add_u64 v[20:21], v[20:21], 2, s[2:3]
	s_waitcnt lgkmcnt(0)
	v_add_f32_e32 v0, v0, v2
	v_mov_b32_e32 v2, v1
	v_mov_b32_e32 v3, v1
	global_store_dwordx4 v[20:21], v[0:3], off
.LBB0_698:
	s_or_b64 exec, exec, s[14:15]
	ds_read_b128 v[20:23], v18 offset:17408
	s_waitcnt lgkmcnt(1)
	v_lshl_add_u64 v[2:3], v[6:7], 0, v[10:11]
	s_waitcnt lgkmcnt(0)
	global_store_dwordx4 v[2:3], v[20:23], off
	v_and_b32_e32 v2, 0xffff0000, v20
	v_lshlrev_b32_e32 v0, 16, v20
	v_mul_f32_e32 v2, v2, v2
	v_lshlrev_b32_e32 v3, 16, v21
	v_fmac_f32_e32 v2, v0, v0
	v_and_b32_e32 v19, 0xffff0000, v21
	v_fmac_f32_e32 v2, v3, v3
	v_lshlrev_b32_e32 v20, 16, v22
	v_fmac_f32_e32 v2, v19, v19
	v_and_b32_e32 v21, 0xffff0000, v22
	v_fmac_f32_e32 v2, v20, v20
	v_lshlrev_b32_e32 v22, 16, v23
	v_fmac_f32_e32 v2, v21, v21
	v_and_b32_e32 v23, 0xffff0000, v23
	v_fmac_f32_e32 v2, v22, v22
	v_fmac_f32_e32 v2, v23, v23
	s_waitcnt lgkmcnt(0)
	s_nop 1
	v_add_f32_dpp v0, v2, v2 quad_perm:[1,0,3,2] row_mask:0xf bank_mask:0xf
	s_waitcnt lgkmcnt(0)
	s_nop 1
	v_add_f32_dpp v0, v0, v0 quad_perm:[2,3,0,1] row_mask:0xf bank_mask:0xf
	s_waitcnt lgkmcnt(0)
	s_nop 1
	v_add_f32_dpp v0, v0, v0 row_half_mirror row_mask:0xf bank_mask:0xf
	s_waitcnt lgkmcnt(0)
	s_nop 1
	v_add_f32_dpp v0, v0, v0 row_mirror row_mask:0xf bank_mask:0xf
	ds_swizzle_b32 v2, v0 offset:swizzle(SWAP,16)
	s_and_saveexec_b64 s[14:15], vcc
	s_cbranch_execz .LBB0_700
	v_lshl_add_u64 v[20:21], v[16:17], 0, 32
	v_lshlrev_b64 v[20:21], s12, v[20:21]
	v_lshl_add_u64 v[20:21], v[20:21], 2, s[2:3]
	s_waitcnt lgkmcnt(0)
	v_add_f32_e32 v0, v0, v2
	v_mov_b32_e32 v2, v1
	v_mov_b32_e32 v3, v1
	global_store_dwordx4 v[20:21], v[0:3], off
.LBB0_700:
	s_or_b64 exec, exec, s[14:15]
	ds_read_b128 v[20:23], v18 offset:26112
	s_waitcnt lgkmcnt(1)
	v_lshl_add_u64 v[2:3], v[6:7], 0, v[8:9]
	s_waitcnt lgkmcnt(0)
	global_store_dwordx4 v[2:3], v[20:23], off
	v_and_b32_e32 v2, 0xffff0000, v20
	v_lshlrev_b32_e32 v0, 16, v20
	v_mul_f32_e32 v2, v2, v2
	v_lshlrev_b32_e32 v3, 16, v21
	v_fmac_f32_e32 v2, v0, v0
	v_and_b32_e32 v19, 0xffff0000, v21
	v_fmac_f32_e32 v2, v3, v3
	v_lshlrev_b32_e32 v20, 16, v22
	v_fmac_f32_e32 v2, v19, v19
	v_and_b32_e32 v21, 0xffff0000, v22
	v_fmac_f32_e32 v2, v20, v20
	v_lshlrev_b32_e32 v22, 16, v23
	v_fmac_f32_e32 v2, v21, v21
	v_and_b32_e32 v23, 0xffff0000, v23
	v_fmac_f32_e32 v2, v22, v22
	v_fmac_f32_e32 v2, v23, v23
	s_waitcnt lgkmcnt(0)
	s_nop 1
	v_add_f32_dpp v0, v2, v2 quad_perm:[1,0,3,2] row_mask:0xf bank_mask:0xf
	s_waitcnt lgkmcnt(0)
	s_nop 1
	v_add_f32_dpp v0, v0, v0 quad_perm:[2,3,0,1] row_mask:0xf bank_mask:0xf
	s_waitcnt lgkmcnt(0)
	s_nop 1
	v_add_f32_dpp v0, v0, v0 row_half_mirror row_mask:0xf bank_mask:0xf
	s_waitcnt lgkmcnt(0)
	s_nop 1
	v_add_f32_dpp v0, v0, v0 row_mirror row_mask:0xf bank_mask:0xf
	ds_swizzle_b32 v2, v0 offset:swizzle(SWAP,16)
	s_and_saveexec_b64 s[14:15], vcc
	s_cbranch_execz .LBB0_693
	v_lshl_add_u64 v[16:17], v[16:17], 0, 48
	v_lshlrev_b64 v[16:17], s12, v[16:17]
	v_lshl_add_u64 v[16:17], v[16:17], 2, s[2:3]
	s_waitcnt lgkmcnt(0)
	v_add_f32_e32 v0, v0, v2
	v_mov_b32_e32 v2, v1
	v_mov_b32_e32 v3, v1
	global_store_dwordx4 v[16:17], v[0:3], off
	s_branch .LBB0_693
